# k3 conversion split 20 per single-item attention workgroup; waves 4-7 of the rwkv prep start 120x64 cycles late
# baseline (speedup 1.0000x reference)
; __device__ __forceinline__ void convert_layer(const Params& p, const Lt& lt, int l, int glo, int ghi, int c, int nc, float* tile) {
;     unsigned char* ws = p.ws;
; #pragma unroll 1
;     for (int m = 0; m < 4; ++m) {
;         const int off = m == 0 ? 0 : (m == 1 ? 608 : (m == 2 ? 864 : 1888)), n = m == 0 ? 608 : (m == 1 ? 256 : 1024);
;         const int lo = (glo > off ? glo : off) - off, hi = (ghi < off + n ? ghi : off + n) - off;
;         if (lo >= hi) continue;
;         const float* src = m == 0 ? p.in[2] + (size_t)l * DM * INC : (m == 1 ? p.in[21] + (size_t)l * DM * DM : (m == 2 ? p.in[23] + (size_t)l * DM * DFF : p.in[24] + (size_t)l * DFF * DM));
;         bf16_t* dst = (bf16_t*)(m == 0 ? ws + WS_WIN + l * SZ_WIN : (m == 1 ? ws + WS_WOUT + l * SZ_WOUT : (m == 2 ? ws + WS_WUP + l * SZ_WUP : ws + WS_WDN + l * SZ_WDN)));
;         const float* scale = m == 0 ? p.in[1] + l * DM : (m == 2 ? p.in[22] + l * DM : nullptr);
;         const int K = m == 3 ? DFF : DM, N = m == 0 ? INC : (m == 2 ? DFF : DM);
;         transpose_big(lt, src, dst, scale, K, N, lo, hi, off - glo, c, nc, tile);
; template <bool COOP>
; __global__ void __launch_bounds__(NTHREADS, 2) mega(Params p0) {
;     ...
;                     if (G == 256 && l + 1 < DEPTH && !(ph0 & 1) && b0 >= 64) convert_layer(p, lt, l + 1, 0, 864, b0 - 64, nat - 64, (float*)lds);
.LBB0_228:
	v_readlane_b32 s0, v253, 52
	v_readlane_b32 s1, v253, 53
	s_andn2_b64 vcc, exec, s[0:1]
	s_cbranch_vccnz .LBB0_259
	s_cmp_gt_i32 s60, 27
	s_cselect_b64 s[0:1], -1, 0
	s_cmpk_lt_i32 s86, 0x30
	s_cselect_b64 s[4:5], -1, 0
	s_or_b64 s[0:1], s[0:1], s[4:5]
	s_and_b64 vcc, exec, s[0:1]
	s_cbranch_vccnz .LBB0_259
	v_readlane_b32 s37, v254, 1
	s_add_i32 s37, s37, 1
	s_mov_b32 s38, 2
	s_cmpk_lt_u32 s86, 0xe0
	s_cbranch_scc1 .Lc3_heavy
	s_add_i32 s34, s86, 0xffffff20
	s_movk_i32 s35, 0x280
	s_movk_i32 s36, 0x20
	s_branch .Lconv_entry
.Lc3_heavy:
	s_add_i32 s34, s86, 0x250
	s_movk_i32 s35, 0x360
	s_movk_i32 s36, 0xb0
	s_branch .Lconv_entry

; __device__ __forceinline__ void rwkv_prep_item(const Params& p, const Lt& lt, int l, int item) {
;     const int tid = lt.tid, lane = tid & 63, w = __builtin_amdgcn_readfirstlane(tid >> 6), qi = lane & 15, quad = lane >> 4;
;     const int t = item * 32 + (w >> 2) * 16 + qi, hg = w & 3;
;     const bf16_t* P = (const bf16_t*)(p.ws + WS_P);
;     const bf16_t* pt = P + (size_t)t * INC;
;     const bf16_t* pp = P + (size_t)(t > 0 ? t - 1 : 0) * INC;
;     const float pm = t > 0 ? 1.f : 0.f;
;     const float* mu = p.in[3] + l * 2560;
;     const bf16_t* lora = (const bf16_t*)(p.ws + WS_LORA + l * SZ_LORA);
;     const bf16_t* decT = lora; const bf16_t* aT = lora + 49152; const bf16_t* gT = lora + 98304;
; template <bool COOP>
; __global__ void __launch_bounds__(NTHREADS, 2) mega(Params p0) {
;     ...
;                 for (int it = lt.bid; it < 256; it += G) {
;                     Lt li = lt; asm volatile("" : "+v"(li.tid));
;                     if (SEL(4)) rwkv_prep_item(p, li, l, G == 256 ? 2 * (it & 127) + (it >> 7) : it);
.LBB0_338:
	s_andn2_b64 vcc, exec, s[0:1]
	s_mov_b64 s[6:7], 0
	s_cbranch_vccnz .LBB0_352
	v_readlane_b32 s0, v254, 3
	s_cmp_gt_i32 s0, 0
	s_mov_b64 s[0:1], -1
	s_cbranch_scc0 .LBB0_350
	s_cmpk_gt_i32 s86, 0xff
	s_cbranch_scc1 .LBB0_349
	v_readlane_b32 s0, v254, 1
	s_add_u32 s6, s62, 0x1ef00000
	v_readlane_b32 s1, v254, 2
	s_mov_b32 s4, s0
	s_mulk_i32 s0, 0xa00
	s_addc_u32 s7, s63, 0
	s_ashr_i32 s1, s0, 31
	v_readlane_b32 s36, v252, 60
	s_lshl_b64 s[0:1], s[0:1], 2
	v_readlane_b32 s42, v253, 2
	v_readlane_b32 s43, v253, 3
	s_add_u32 s8, s42, s0
	s_addc_u32 s9, s43, s1
	s_ashr_i32 s5, s4, 31
	s_lshl_b64 s[0:1], s[4:5], 19
	s_add_u32 s0, s62, s0
	s_addc_u32 s1, s63, s1
	s_add_u32 s28, s0, 0x16c00000
	s_addc_u32 s29, s1, 0
	s_add_u32 s30, s0, 0x16c18000
	s_addc_u32 s31, s1, 0
	s_add_u32 s34, s0, 0x16c30000
	s_addc_u32 s35, s1, 0
	v_readlane_b32 s37, v252, 61
	s_add_u32 s36, s62, 0x23b00000
	v_readlane_b32 s38, v252, 62
	s_addc_u32 s37, s63, 0
	v_readlane_b32 s39, v252, 63
	s_add_u32 s38, s62, 0x28f00000
	s_mov_b32 s0, s4
	v_readlane_b32 s40, v253, 0
	s_addc_u32 s39, s63, 0
	v_writelane_b32 v254, s0, 1
	v_readlane_b32 s41, v253, 1
	s_add_u32 s40, s62, 0x2a700000
	v_writelane_b32 v254, s1, 2
	s_mul_i32 s0, s4, 0x300
	s_addc_u32 s41, s63, 0
	s_ashr_i32 s1, s0, 31
	v_readlane_b32 s44, v253, 4
	s_lshl_b64 s[0:1], s[0:1], 2
	v_readlane_b32 s45, v253, 5
	s_add_u32 s42, s44, s0
	v_readlane_b32 s48, v253, 8
	s_addc_u32 s43, s45, s1
	v_readlane_b32 s49, v253, 9
	v_readlane_b32 s50, v253, 10
	v_readlane_b32 s51, v253, 11
	s_add_u32 s44, s48, s0
	s_addc_u32 s45, s49, s1
	v_readlane_b32 s48, v253, 27
	v_readlane_b32 s46, v253, 6
	v_readlane_b32 s50, v253, 29
	v_readlane_b32 s47, v253, 7
	v_readlane_b32 s51, v253, 30
	s_add_u32 s46, s50, s0
	v_readlane_b32 s52, v253, 31
	s_addc_u32 s47, s51, s1
	v_readlane_b32 s49, v253, 28
	v_readlane_b32 s53, v253, 32
	s_add_u32 s48, s52, s0
	v_readlane_b32 s54, v253, 33
	s_addc_u32 s49, s53, s1
	v_readlane_b32 s55, v253, 34
	s_add_u32 s50, s54, s0
	s_addc_u32 s51, s55, s1
	v_readlane_b32 s60, v253, 39
	s_add_u32 s52, s8, 0x1800
	v_readlane_b32 s60, v253, 62
	s_addc_u32 s53, s9, 0
	s_lshl_b32 s54, s86, 1
	s_mov_b32 s55, s86
	v_readlane_b32 s56, v253, 35
	v_readlane_b32 s57, v253, 36
	v_readlane_b32 s58, v253, 37
	v_readlane_b32 s59, v253, 38
	v_readlane_b32 s61, v253, 40
	v_readlane_b32 s62, v253, 41
	v_readlane_b32 s63, v253, 42
	v_readfirstlane_b32 s0, v245
	s_bitcmp1_b32 s0, 8
	s_cbranch_scc0 .Lprep_nostagger
	s_sleep 120
.Lprep_nostagger:
	s_branch .LBB0_343
.LBB0_342:
	s_or_b64 exec, exec, s[0:1]
	v_readlane_b32 s0, v252, 51
	s_add_i32 s55, s55, s89
	s_add_i32 s54, s54, s0
	s_cmpk_gt_i32 s55, 0xff
	s_cbranch_scc1 .LBB0_349
